# weight conversion hidden in three GEMM imbalance slots (in-proj: next-layer w13; FFN2-up: next-layer w2/wq/wo/mixer; FFN1-up: own FFN2 weights), standalone phase + sync removed
# speedup vs baseline: 1.0140x; 1.0140x over previous
; #define EWA_REP for (int rep_ = 0; rep_ < 2; ++rep_)
; __device__ __forceinline__ void conv_item(const float* __restrict__ W, const float* __restrict__ g, int K, int NS, int NP, bf16_t* __restrict__ dst, int ldd, int koff, int row_off, int ilv,
;                                           LAS float* scr, int item, int lane) {
;     ...
;     const int nblk = (NP + 127) / 128, kb = item / nblk, nb = item % nblk, k0 = 64 * kb, n0 = 128 * nb, n = n0 + lane * 2;
;     const bool rd = (W != nullptr) && (n < NS);
; #pragma unroll 1
;     for (int b2 = 0; b2 < 2; ++b2) {
;         f32x2 v[32];
; #pragma unroll
;         for (int r = 0; r < 32; ++r) {
;             const int k = k0 + b2 * 32 + r;
; __global__ void __launch_bounds__(512, 2) mega_fwd(KArgs a) {
;     ...
;     for (int l = 0; l < NL; ++l) {
;         const int j = l >> 1; const bool even = (l & 1) == 0;
;         if (l > 0) { { PH_VARS EWA_REP { CONV_LAYER(l); } } GSYNC(); }
.LBB0_1764:
	s_lshr_b32 s0, s1, 1
	v_writelane_b32 v252, s0, 25
	s_and_b32 s0, s1, 1
	s_cmp_eq_u32 s0, 0
	s_cselect_b64 s[12:13], -1, 0
	s_cmp_eq_u32 s0, 1
	s_cselect_b64 s[2:3], -1, 0
	s_cmp_eq_u32 s1, 0
	s_cselect_b64 s[6:7], -1, 0
	v_writelane_b32 v252, s1, 26
	s_and_b64 vcc, exec, s[6:7]
	s_cbranch_vccnz .LBB0_3143
	s_cmpk_lt_u32 s86, 0x80
	s_cbranch_scc1 .LBB0_3143
	v_writelane_b32 v254, 1, 40
	v_readlane_b32 vcc_lo, v252, 26
	s_nop 1
	s_and_b32 vcc_lo, vcc_lo, 1
	v_writelane_b32 v254, vcc_lo, 41
.Lmy_conv_pre:
	s_mov_b64 s[0:1], s[88:89]
	v_mov_b32_e32 v1, v220
	s_movk_i32 s11, 0x70
	v_and_b32_e32 v4, 63, v1
	v_readfirstlane_b32 s4, v1
	s_waitcnt vmcnt(9)
	v_and_b32_e32 v70, 7, v1
	v_lshlrev_b32_e32 v5, 4, v4
	v_lshlrev_b32_e32 v2, 3, v1
	v_bfe_u32 v72, v1, 3, 3
	v_or_b32_e32 v1, 64, v4
	v_lshrrev_b32_e32 v75, 3, v1
	v_bitop3_b32 v77, v1, s11, v5 bitop3:0x48
	v_or_b32_e32 v1, 0xc0, v4
	v_lshrrev_b32_e32 v80, 3, v1
	v_bitop3_b32 v82, v1, s11, v5 bitop3:0x48
	v_or_b32_e32 v1, 0x140, v4
	v_lshrrev_b32_e32 v85, 3, v1
	v_bitop3_b32 v87, v1, s11, v5 bitop3:0x48
	v_or_b32_e32 v1, 0x1c0, v4
	s_waitcnt vmcnt(8)
	v_lshrrev_b32_e32 v90, 3, v1
	v_bitop3_b32 v92, v1, s11, v5 bitop3:0x48
	v_or_b32_e32 v1, 0x240, v4
	v_lshrrev_b32_e32 v95, 3, v1
	v_bitop3_b32 v97, v1, s11, v5 bitop3:0x48
	v_or_b32_e32 v1, 0x2c0, v4
	s_ashr_i32 s4, s4, 6
	v_readlane_b32 s5, v252, 0
	v_lshrrev_b32_e32 v100, 3, v1
	v_bitop3_b32 v102, v1, s11, v5 bitop3:0x48
	v_or_b32_e32 v1, 0x340, v4
	s_add_i32 s48, s4, s5
	s_lshl_b32 s4, s4, 14
	v_lshrrev_b32_e32 v105, 3, v1
	v_bitop3_b32 v107, v1, s11, v5 bitop3:0x48
	v_or_b32_e32 v1, 0x3c0, v4
	v_readlane_b32 s26, v252, 25
	s_add_i32 s10, s4, 0
	v_readlane_b32 s14, v252, 26
	v_readlane_b32 s15, v254, 40
	s_nop 1
	s_lshr_b32 s15, s15, 1
	s_add_i32 s14, s14, s15
	s_lshr_b32 s26, s14, 1
	v_or_b32_e32 v78, 16, v72
	v_or_b32_e32 v83, 32, v72
	v_or_b32_e32 v88, 48, v72
	v_or_b32_e32 v93, 64, v72
	v_or_b32_e32 v98, 0x50, v72
	v_or_b32_e32 v103, 0x60, v72
	v_or_b32_e32 v108, 0x70, v72
	v_lshrrev_b32_e32 v110, 3, v1
	s_mul_i32 s16, s26, 0x1b2000
	s_mov_b32 s17, s68
	s_lshl_b32 s18, s26, 20
	s_mov_b32 s19, s68
	s_mul_i32 s20, s26, 0x2a8000
	s_mov_b32 s21, s68
	s_mul_i32 s22, s26, 0x30000
	s_mov_b32 s23, s68
	s_lshl_b32 s24, s26, 17
	s_mov_b32 s25, s68
	s_mul_i32 s26, s26, 0xc0000
	s_mov_b32 s27, s68
	s_mul_i32 s4, s14, 0x580000
	s_mov_b32 s5, s68
	s_lshl_b32 s8, s14, 10
	s_mov_b32 s9, s68
	s_waitcnt lgkmcnt(0)
	v_lshlrev_b32_e32 v3, 1, v4
	v_lshl_add_u32 v71, v4, 8, s10
	v_and_b32_e32 v2, 56, v2
	v_bitop3_b32 v73, v5, s11, v4 bitop3:0x48
	v_lshl_add_u32 v74, v72, 7, s10
	v_lshl_add_u32 v76, v75, 7, s10
	v_lshl_add_u32 v79, v78, 7, s10
	v_lshl_add_u32 v81, v80, 7, s10
	v_lshl_add_u32 v84, v83, 7, s10
	v_lshl_add_u32 v86, v85, 7, s10
	v_lshl_add_u32 v89, v88, 7, s10
	v_lshl_add_u32 v91, v90, 7, s10
	v_lshl_add_u32 v94, v93, 7, s10
	v_lshl_add_u32 v96, v95, 7, s10
	v_lshl_add_u32 v99, v98, 7, s10
	v_lshl_add_u32 v101, v100, 7, s10
	v_lshl_add_u32 v104, v103, 7, s10
	v_lshl_add_u32 v106, v105, 7, s10
	v_lshl_add_u32 v109, v108, 7, s10
	v_lshl_add_u32 v111, v110, 7, s10
	v_bitop3_b32 v112, v1, s11, v5 bitop3:0x48
	s_mul_i32 s10, s14, 0x2c0000
	s_mov_b32 s11, s68
	s_lshl_b32 s14, s14, 20
	s_mov_b32 s15, s68
	s_lshl_b64 s[16:17], s[16:17], 2
	s_lshl_b64 s[18:19], s[18:19], 2
	s_lshl_b64 s[20:21], s[20:21], 2
	s_lshl_b64 s[22:23], s[22:23], 2
	s_lshl_b64 s[24:25], s[24:25], 2
	s_lshl_b64 s[26:27], s[26:27], 2
	v_readlane_b32 s28, v254, 40
	s_nop 1
	s_cmp_eq_u32 s28, 2
	s_cbranch_scc1 .Lmy_conv_s2
	s_cmp_eq_u32 s28, 3
	s_cbranch_scc1 .Lmy_conv_s3
	s_addk_i32 s48, 0x20
	s_branch .Lmy_conv_s0
.Lmy_conv_s2:
	s_addk_i32 s48, 0xfa00
	s_branch .Lmy_conv_s0
.Lmy_conv_s3:
	s_addk_i32 s48, 0xfec0

.LBB0_1767:
	v_readlane_b32 s28, v254, 40
	s_nop 1
	s_cmp_eq_u32 s28, 2
	s_cbranch_scc1 .Lmy_d2
	s_cmp_eq_u32 s28, 3
	s_cbranch_scc1 .Lmy_d3
	s_cmpk_ge_i32 s48, 2112
	s_cbranch_scc1 .LBB0_3090
	s_branch .Lmy_conv_disp
.Lmy_d2:
	s_cmpk_ge_i32 s48, 704
	s_cbranch_scc1 .LBB0_3090
	s_branch .Lmy_conv_disp
.Lmy_d3:
	s_cmpk_lt_i32 s48, 1056
	s_cbranch_scc1 .Lmy_conv_disp
	s_cmpk_ge_i32 s48, 2112
	s_cbranch_scc1 .Lmy_conv_disp
	s_addk_i32 s48, 1056

.LBB0_2391:
	v_readlane_b32 s30, v254, 41
	s_nop 1
	s_cmp_eq_u32 s30, 0
	s_cbranch_scc1 .LBB0_2395
	s_cmpk_gt_i32 s49, 0xdf
	s_cselect_b64 s[28:29], -1, 0
	s_mov_b64 s[30:31], -1
	s_and_b64 vcc, exec, s[28:29]
	s_cbranch_vccz .LBB0_2400
	s_mov_b32 s36, 53
	s_and_b64 vcc, exec, s[30:31]
	s_mov_b32 s37, s49
	s_cbranch_vccnz .LBB0_2569

; #define LAS __attribute__((address_space(3)))
; __device__ __forceinline__ void conv_item(const float* __restrict__ W, const float* __restrict__ g, int K, int NS, int NP, bf16_t* __restrict__ dst, int ldd, int koff, int row_off, int ilv,
;                                           LAS float* scr, int item, int lane) {
;     ...
;             v[r] = rd ? __builtin_nontemporal_load((const f32x2*)(W + (size_t)k * NS + n)) : (f32x2){0.f, 0.f};
;     ...
;     for (int j = 0; j < 16; ++j) {
;         const int idx = j * 64 + lane, nl = idx >> 3, q = idx & 7, nn = n0 + nl;
;         const u32x4 o = *(const LAS u32x4*)(tile + nl * 128 + ((q ^ ((nl >> 1) & 7)) << 4));
;         if (nn < NP) {
;             const int drow = row_off + (ilv ? (nn < ilv ? 2 * nn : 2 * (nn - ilv) + 1) : nn);
;             *(u32x4*)(dst + (size_t)drow * ldd + koff + k0 + q * 8) = o;
;         }
.LBB0_2874:
	s_or_b64 exec, exec, s[44:45]
	v_mov_b32_e32 v67, 0
	s_and_saveexec_b64 s[44:45], s[38:39]
	s_cbranch_execz .LBB0_2811
	s_or_b32 s42, s42, 31
	s_ashr_i32 s43, s42, 31
	s_lshl_b64 s[42:43], s[42:43], 12
	v_lshl_add_u64 v[66:67], v[4:5], 0, s[42:43]
	global_load_dwordx2 v[66:67], v[66:67], off nt
	s_branch .LBB0_2811
.Lmy_isl_f3:
	s_branch .Lmy_conv_pre
.LBB0_2876:
	s_ashr_i32 s37, s36, 31
	s_lshl_b64 s[36:37], s[36:37], 1
	s_add_u32 s34, s34, s36
	s_waitcnt lgkmcnt(0)
	s_addc_u32 s35, s35, s37
	v_lshlrev_b32_e32 v4, 1, v2
	v_mov_b32_e32 v5, v0
	v_lshl_add_u64 v[4:5], s[34:35], 0, v[4:5]
	s_mov_b64 s[34:35], 0x2a80200
	v_or_b32_e32 v1, s46, v72
	v_lshl_add_u64 v[4:5], v[4:5], 0, s[34:35]
	v_cmp_gt_i32_e32 vcc, s95, v1
	s_and_saveexec_b64 s[34:35], vcc
	s_cbranch_execz .LBB0_2878
	v_add_u32_e32 v6, v74, v73
	s_movk_i32 s36, 0x180
	ds_read_b128 v[6:9], v6
	v_mul_lo_u32 v10, v1, s36
	v_ashrrev_i32_e32 v11, 31, v10
	v_lshl_add_u64 v[10:11], v[10:11], 1, v[4:5]
	v_add_co_u32_e32 v10, vcc, 0x90000, v10
	s_nop 1
	v_addc_co_u32_e32 v11, vcc, 0, v11, vcc
	s_waitcnt lgkmcnt(0)
	global_store_dwordx4 v[10:11], v[6:9], off

; #define EWA_REP for (int rep_ = 0; rep_ < 2; ++rep_)
; __global__ void __launch_bounds__(512, 2) mega_fwd(KArgs a) {
;     ...
;         if (l > 0) { { PH_VARS EWA_REP { CONV_LAYER(l); } } GSYNC(); }
.LBB0_3090:
	v_readlane_b32 s4, v254, 40
	s_nop 1
	s_cmp_eq_u32 s4, 2
	s_cbranch_scc1 .Lmy_conv3_done
	s_cmp_eq_u32 s4, 3
	s_cbranch_scc1 .Lmy_isl_r1
	s_waitcnt lgkmcnt(0)
	s_barrier

; #define KA_DEF const __attribute__((address_space(4))) KArgs* ka_ = (const __attribute__((address_space(4))) KArgs*)__builtin_amdgcn_kernarg_segment_ptr(); asm volatile("" : "+s"(ka_));
; #define SSQ ((float*)WSP(WS_SSQ))
; __global__ void __launch_bounds__(512, 2) mega_fwd(KArgs a) {
;     ...
;         { KA_DEF pg8::EpiBf16S E{RA, ldc, SSQ}; run_gemm(TIDX, lds, XB, Wl + WO_WIN, T_, ldc, 1024, E); }
.LBB0_3324:
	s_or_b64 exec, exec, s[0:1]
	s_mov_b64 s[0:1], s[88:89]
	s_waitcnt lgkmcnt(0)
	s_barrier
	s_cmpk_lt_u32 s86, 0xc0
	s_cbranch_scc1 .Lmy_inproj_go
	v_readlane_b32 vcc_lo, v252, 26
	s_nop 1
	s_cmp_eq_u32 vcc_lo, 3
	s_cbranch_scc1 .Lmy_inproj_go
	v_writelane_b32 v254, 2, 40
	s_add_i32 vcc_lo, vcc_lo, 1
	s_and_b32 vcc_lo, vcc_lo, 1
	v_writelane_b32 v254, vcc_lo, 41
	s_branch .Lmy_conv_pre

; __global__ void __launch_bounds__(512, 2) mega_fwd(KArgs a) {
;     ...
; #pragma unroll 1
;     ...
;                     const unsigned cand = tau | (1u << bit);
;                     int c0 = 0, c1 = 0;
; #pragma unroll
;                     for (int jj = 0; jj < 64; ++jj) { const unsigned long long bm = __ballot(key[jj] >= cand); c0 += __popc((unsigned)bm); c1 += __popc((unsigned)(bm >> 32)); }
;                     const int cnt = (lane < 32) ? c0 : c1;
;                     if (cnt >= 256) tau = cand;
;                     done_sel = done_sel || (cnt == 256);
;                     if (__ballot(!done_sel) == 0ull) break;
;                 }
.Lmy_sel_loop_8:
	v_lshl_or_b32 v12, 1, v11, v10
	v_mov_b32_e32 v13, 0
	v_cmp_ge_u32_e64 s[84:85], v3, v12
	v_cmp_ge_u32_e64 s[76:77], v2, v12
	v_cmp_ge_u32_e64 s[74:75], v5, v12
	v_addc_co_u32_e64 v13, vcc, 0, v13, s[84:85]
	v_cmp_ge_u32_e64 s[84:85], v4, v12
	v_addc_co_u32_e64 v13, vcc, 0, v13, s[76:77]
	v_cmp_ge_u32_e64 s[76:77], v7, v12
	v_addc_co_u32_e64 v13, vcc, 0, v13, s[74:75]
	v_cmp_ge_u32_e64 s[74:75], v6, v12
	v_addc_co_u32_e64 v13, vcc, 0, v13, s[84:85]
	v_cmp_ge_u32_e64 s[84:85], v9, v12
	v_addc_co_u32_e64 v13, vcc, 0, v13, s[76:77]
	v_cmp_ge_u32_e64 s[76:77], v8, v12
	v_addc_co_u32_e64 v13, vcc, 0, v13, s[74:75]
	v_cmp_ge_u32_e64 s[74:75], v102, v12
	v_addc_co_u32_e64 v13, vcc, 0, v13, s[84:85]
	v_cmp_ge_u32_e64 s[84:85], v97, v12
	v_addc_co_u32_e64 v13, vcc, 0, v13, s[76:77]
	v_cmp_ge_u32_e64 s[76:77], v104, v12
	v_addc_co_u32_e64 v13, vcc, 0, v13, s[74:75]
	v_cmp_ge_u32_e64 s[74:75], v99, v12
	v_addc_co_u32_e64 v13, vcc, 0, v13, s[84:85]
	v_cmp_ge_u32_e64 s[84:85], v106, v12
	v_addc_co_u32_e64 v13, vcc, 0, v13, s[76:77]
	v_cmp_ge_u32_e64 s[76:77], v101, v12
	v_addc_co_u32_e64 v13, vcc, 0, v13, s[74:75]
	v_cmp_ge_u32_e64 s[74:75], v108, v12
	v_addc_co_u32_e64 v13, vcc, 0, v13, s[84:85]
	v_cmp_ge_u32_e64 s[84:85], v103, v12
	v_addc_co_u32_e64 v13, vcc, 0, v13, s[76:77]
	v_cmp_ge_u32_e64 s[76:77], v110, v12
	v_addc_co_u32_e64 v13, vcc, 0, v13, s[74:75]
	v_cmp_ge_u32_e64 s[74:75], v105, v12
	v_addc_co_u32_e64 v13, vcc, 0, v13, s[84:85]
	v_cmp_ge_u32_e64 s[84:85], v112, v12
	v_addc_co_u32_e64 v13, vcc, 0, v13, s[76:77]
	v_cmp_ge_u32_e64 s[76:77], v107, v12
	v_addc_co_u32_e64 v13, vcc, 0, v13, s[74:75]
	v_cmp_ge_u32_e64 s[74:75], v114, v12
	v_addc_co_u32_e64 v13, vcc, 0, v13, s[84:85]
	v_cmp_ge_u32_e64 s[84:85], v109, v12
	v_addc_co_u32_e64 v13, vcc, 0, v13, s[76:77]
	v_cmp_ge_u32_e64 s[76:77], v116, v12
	v_addc_co_u32_e64 v13, vcc, 0, v13, s[74:75]
	v_cmp_ge_u32_e64 s[74:75], v111, v12
	v_addc_co_u32_e64 v13, vcc, 0, v13, s[84:85]
	v_cmp_ge_u32_e64 s[84:85], v118, v12
	v_addc_co_u32_e64 v13, vcc, 0, v13, s[76:77]
	v_cmp_ge_u32_e64 s[76:77], v113, v12
	v_addc_co_u32_e64 v13, vcc, 0, v13, s[74:75]
	v_cmp_ge_u32_e64 s[74:75], v120, v12
	v_addc_co_u32_e64 v13, vcc, 0, v13, s[84:85]
	v_cmp_ge_u32_e64 s[84:85], v115, v12
	v_addc_co_u32_e64 v13, vcc, 0, v13, s[76:77]
	v_cmp_ge_u32_e64 s[76:77], v122, v12
	v_addc_co_u32_e64 v13, vcc, 0, v13, s[74:75]
	v_cmp_ge_u32_e64 s[74:75], v117, v12
	v_addc_co_u32_e64 v13, vcc, 0, v13, s[84:85]
	v_cmp_ge_u32_e64 s[84:85], v124, v12
	v_addc_co_u32_e64 v13, vcc, 0, v13, s[76:77]
	v_cmp_ge_u32_e64 s[76:77], v119, v12
	v_addc_co_u32_e64 v13, vcc, 0, v13, s[74:75]
	v_cmp_ge_u32_e64 s[74:75], v158, v12
	v_addc_co_u32_e64 v13, vcc, 0, v13, s[84:85]
	v_cmp_ge_u32_e64 s[84:85], v121, v12
	v_addc_co_u32_e64 v13, vcc, 0, v13, s[76:77]
	v_cmp_ge_u32_e64 s[76:77], v160, v12
	v_addc_co_u32_e64 v13, vcc, 0, v13, s[74:75]
	v_cmp_ge_u32_e64 s[74:75], v123, v12
	v_addc_co_u32_e64 v13, vcc, 0, v13, s[84:85]
	v_cmp_ge_u32_e64 s[84:85], v162, v12
	v_addc_co_u32_e64 v13, vcc, 0, v13, s[76:77]
	v_cmp_ge_u32_e64 s[76:77], v125, v12
	v_addc_co_u32_e64 v13, vcc, 0, v13, s[74:75]
	v_cmp_ge_u32_e64 s[74:75], v164, v12
	v_addc_co_u32_e64 v13, vcc, 0, v13, s[84:85]
	v_cmp_ge_u32_e64 s[84:85], v159, v12
	v_addc_co_u32_e64 v13, vcc, 0, v13, s[76:77]
	v_cmp_ge_u32_e64 s[76:77], v168, v12
	v_addc_co_u32_e64 v13, vcc, 0, v13, s[74:75]
	v_cmp_ge_u32_e64 s[74:75], v161, v12
	v_addc_co_u32_e64 v13, vcc, 0, v13, s[84:85]
	v_cmp_ge_u32_e64 s[84:85], v170, v12
	v_addc_co_u32_e64 v13, vcc, 0, v13, s[76:77]
	v_cmp_ge_u32_e64 s[76:77], v163, v12
	v_addc_co_u32_e64 v13, vcc, 0, v13, s[74:75]
	v_cmp_ge_u32_e64 s[74:75], v172, v12
	v_addc_co_u32_e64 v13, vcc, 0, v13, s[84:85]
	v_cmp_ge_u32_e64 s[84:85], v165, v12
	v_addc_co_u32_e64 v13, vcc, 0, v13, s[76:77]
	v_cmp_ge_u32_e64 s[76:77], v174, v12
	v_addc_co_u32_e64 v13, vcc, 0, v13, s[74:75]
	v_cmp_ge_u32_e64 s[74:75], v169, v12
	v_addc_co_u32_e64 v13, vcc, 0, v13, s[84:85]
	v_cmp_ge_u32_e64 s[84:85], v176, v12
	v_addc_co_u32_e64 v13, vcc, 0, v13, s[76:77]
	v_cmp_ge_u32_e64 s[76:77], v171, v12
	v_addc_co_u32_e64 v13, vcc, 0, v13, s[74:75]
	v_cmp_ge_u32_e64 s[74:75], v178, v12
	v_addc_co_u32_e64 v13, vcc, 0, v13, s[84:85]
	v_cmp_ge_u32_e64 s[84:85], v173, v12
	v_addc_co_u32_e64 v13, vcc, 0, v13, s[76:77]
	v_cmp_ge_u32_e64 s[76:77], v180, v12
	v_addc_co_u32_e64 v13, vcc, 0, v13, s[74:75]
	v_cmp_ge_u32_e64 s[74:75], v175, v12
	v_addc_co_u32_e64 v13, vcc, 0, v13, s[84:85]
	v_cmp_ge_u32_e64 s[84:85], v182, v12
	v_addc_co_u32_e64 v13, vcc, 0, v13, s[76:77]
	v_cmp_ge_u32_e64 s[76:77], v177, v12
	v_addc_co_u32_e64 v13, vcc, 0, v13, s[74:75]
	v_cmp_ge_u32_e64 s[74:75], v184, v12
	v_addc_co_u32_e64 v13, vcc, 0, v13, s[84:85]
	v_cmp_ge_u32_e64 s[84:85], v179, v12
	v_addc_co_u32_e64 v13, vcc, 0, v13, s[76:77]
	v_cmp_ge_u32_e64 s[76:77], v186, v12
	v_addc_co_u32_e64 v13, vcc, 0, v13, s[74:75]
	v_cmp_ge_u32_e64 s[74:75], v181, v12
	v_addc_co_u32_e64 v13, vcc, 0, v13, s[84:85]
	v_cmp_ge_u32_e64 s[84:85], v188, v12
	v_addc_co_u32_e64 v13, vcc, 0, v13, s[76:77]
	v_cmp_ge_u32_e64 s[76:77], v183, v12
	v_addc_co_u32_e64 v13, vcc, 0, v13, s[74:75]
	v_cmp_ge_u32_e64 s[74:75], v190, v12
	v_addc_co_u32_e64 v13, vcc, 0, v13, s[84:85]
	v_cmp_ge_u32_e64 s[84:85], v185, v12
	s_nop 1
	v_addc_co_u32_e64 v13, vcc, 0, v13, s[76:77]
	v_addc_co_u32_e64 v13, vcc, 0, v13, s[74:75]
	v_addc_co_u32_e64 v13, vcc, 0, v13, s[84:85]
	s_nop 1
	v_add_u32_dpp v13, v13, v13 quad_perm:[1,0,3,2] row_mask:0xf bank_mask:0xf
	s_nop 1
	v_add_u32_dpp v13, v13, v13 quad_perm:[2,3,0,1] row_mask:0xf bank_mask:0xf
	s_nop 1
	v_add_u32_dpp v13, v13, v13 row_half_mirror row_mask:0xf bank_mask:0xf
	s_nop 1
	v_add_u32_dpp v13, v13, v13 row_mirror row_mask:0xf bank_mask:0xf
	v_mov_b32_e32 v14, v13
	s_nop 1
	v_permlane16_swap_b32 v14, v13
	v_add_u32_e32 v13, v13, v14
	s_movk_i32 s2, 0xff
	v_cmp_lt_i32_e32 vcc, s2, v13
	s_nop 1
	v_cndmask_b32_e32 v10, v10, v12, vcc
	v_cmp_eq_u32_e32 vcc, s5, v13
	s_or_b64 s[0:1], s[0:1], vcc
	s_xor_b64 s[2:3], s[0:1], -1
	v_cndmask_b32_e64 v12, 0, 1, s[2:3]
	v_cmp_ne_u32_e32 vcc, 0, v12
	s_cmp_lg_u64 vcc, 0
	s_cselect_b64 s[2:3], -1, 0
	v_add_co_u32_e32 v11, vcc, -1, v11
	s_and_b64 s[2:3], s[2:3], vcc
	s_and_b64 vcc, exec, s[2:3]
	s_cbranch_vccnz .Lmy_sel_loop_8
	s_andn2_b64 s[2:3], exec, s[0:1]
	s_cbranch_scc0 .Lmy_sel_fast_8
	s_branch .Lmy_sel_slow
; __global__ void __launch_bounds__(512, 2) mega_fwd(KArgs a) {
;     ...
;                 if (all_valid) tau = 1u;
;                 int g0 = 0, g1 = 0, e0 = 0, e1 = 0;
; #pragma unroll
;                 for (int jj = 0; jj < 64; ++jj) {
;                     const unsigned long long bg = __ballot(key[jj] > tau), be = __ballot(key[jj] == tau);
;                     g0 += __popc((unsigned)bg); g1 += __popc((unsigned)(bg >> 32)); e0 += __popc((unsigned)be); e1 += __popc((unsigned)(be >> 32));
;                 }
;                 const int cgt = (lane < 32) ? g0 : g1, ceq = (lane < 32) ? e0 : e1;
;                 const int need_eq = all_valid ? (1 << 20) : 256 - cgt;
;                 const bool ties = (!all_valid) && (ceq > need_eq);
;                 unsigned w0 = 0u, w1 = 0u;
;                 if (__ballot(ties) == 0ull) {
; #pragma unroll
;                     for (int jj = 0; jj < 64; ++jj) {
;                         const unsigned long long bm = __ballot(key[jj] >= tau);
;                         if (lane == 0) { wscr[jj] = (unsigned)bm; wscr[64 + jj] = (unsigned)(bm >> 32); }
;                     }
.Lmy_isl_f2:
	s_branch .Lmy_isl_f3
.Lmy_sel_fast_8:
	v_cndmask_b32_e64 v12, v10, 1, s[86:87]
	v_mov_b32_e32 v13, 0
	v_mov_b32_e32 v14, 0
	v_cmp_ge_u32_e64 s[84:85], v3, v12
	v_cmp_ge_u32_e64 s[76:77], v2, v12
	v_cmp_ge_u32_e64 s[74:75], v5, v12
	v_writelane_b32 v13, s84, 0
	v_writelane_b32 v14, s85, 0
	v_cmp_ge_u32_e64 s[84:85], v4, v12
	v_writelane_b32 v13, s76, 1
	v_writelane_b32 v14, s77, 1
	v_cmp_ge_u32_e64 s[76:77], v7, v12
	v_writelane_b32 v13, s74, 2
	v_writelane_b32 v14, s75, 2
	v_cmp_ge_u32_e64 s[74:75], v6, v12
	v_writelane_b32 v13, s84, 3
	v_writelane_b32 v14, s85, 3
	v_cmp_ge_u32_e64 s[84:85], v9, v12
	v_writelane_b32 v13, s76, 4
	v_writelane_b32 v14, s77, 4
	v_cmp_ge_u32_e64 s[76:77], v8, v12
	v_writelane_b32 v13, s74, 5
	v_writelane_b32 v14, s75, 5
	v_cmp_ge_u32_e64 s[74:75], v102, v12
	v_writelane_b32 v13, s84, 6
	v_writelane_b32 v14, s85, 6
	v_cmp_ge_u32_e64 s[84:85], v97, v12
	v_writelane_b32 v13, s76, 7
	v_writelane_b32 v14, s77, 7
	v_cmp_ge_u32_e64 s[76:77], v104, v12
	v_writelane_b32 v13, s74, 8
	v_writelane_b32 v14, s75, 8
	v_cmp_ge_u32_e64 s[74:75], v99, v12
	v_writelane_b32 v13, s84, 9
	v_writelane_b32 v14, s85, 9
	v_cmp_ge_u32_e64 s[84:85], v106, v12
	v_writelane_b32 v13, s76, 10
	v_writelane_b32 v14, s77, 10
	v_cmp_ge_u32_e64 s[76:77], v101, v12
	v_writelane_b32 v13, s74, 11
	v_writelane_b32 v14, s75, 11
	v_cmp_ge_u32_e64 s[74:75], v108, v12
	v_writelane_b32 v13, s84, 12
	v_writelane_b32 v14, s85, 12
	v_cmp_ge_u32_e64 s[84:85], v103, v12
	v_writelane_b32 v13, s76, 13
	v_writelane_b32 v14, s77, 13
	v_cmp_ge_u32_e64 s[76:77], v110, v12
	v_writelane_b32 v13, s74, 14
	v_writelane_b32 v14, s75, 14
	v_cmp_ge_u32_e64 s[74:75], v105, v12
	v_writelane_b32 v13, s84, 15
	v_writelane_b32 v14, s85, 15
	v_cmp_ge_u32_e64 s[84:85], v112, v12
	v_writelane_b32 v13, s76, 16
	v_writelane_b32 v14, s77, 16
	v_cmp_ge_u32_e64 s[76:77], v107, v12
	v_writelane_b32 v13, s74, 17
	v_writelane_b32 v14, s75, 17
	v_cmp_ge_u32_e64 s[74:75], v114, v12
	v_writelane_b32 v13, s84, 18
	v_writelane_b32 v14, s85, 18
	v_cmp_ge_u32_e64 s[84:85], v109, v12
	v_writelane_b32 v13, s76, 19
	v_writelane_b32 v14, s77, 19
	v_cmp_ge_u32_e64 s[76:77], v116, v12
	v_writelane_b32 v13, s74, 20
	v_writelane_b32 v14, s75, 20
	v_cmp_ge_u32_e64 s[74:75], v111, v12
	v_writelane_b32 v13, s84, 21
	v_writelane_b32 v14, s85, 21
	v_cmp_ge_u32_e64 s[84:85], v118, v12
	v_writelane_b32 v13, s76, 22
	v_writelane_b32 v14, s77, 22
	v_cmp_ge_u32_e64 s[76:77], v113, v12
	v_writelane_b32 v13, s74, 23
	v_writelane_b32 v14, s75, 23
	v_cmp_ge_u32_e64 s[74:75], v120, v12
	v_writelane_b32 v13, s84, 24
	v_writelane_b32 v14, s85, 24
	v_cmp_ge_u32_e64 s[84:85], v115, v12
	v_writelane_b32 v13, s76, 25
	v_writelane_b32 v14, s77, 25
	v_cmp_ge_u32_e64 s[76:77], v122, v12
	v_writelane_b32 v13, s74, 26
	v_writelane_b32 v14, s75, 26
	v_cmp_ge_u32_e64 s[74:75], v117, v12
	v_writelane_b32 v13, s84, 27
	v_writelane_b32 v14, s85, 27
	v_cmp_ge_u32_e64 s[84:85], v124, v12
	v_writelane_b32 v13, s76, 28
	v_writelane_b32 v14, s77, 28
	v_cmp_ge_u32_e64 s[76:77], v119, v12
	v_writelane_b32 v13, s74, 29
	v_writelane_b32 v14, s75, 29
	v_cmp_ge_u32_e64 s[74:75], v158, v12
	v_writelane_b32 v13, s84, 30
	v_writelane_b32 v14, s85, 30
	v_cmp_ge_u32_e64 s[84:85], v121, v12
	v_writelane_b32 v13, s76, 31
	v_writelane_b32 v14, s77, 31
	v_cmp_ge_u32_e64 s[76:77], v160, v12
	v_writelane_b32 v13, s74, 32
	v_writelane_b32 v14, s75, 32
	v_cmp_ge_u32_e64 s[74:75], v123, v12
	v_writelane_b32 v13, s84, 33
	v_writelane_b32 v14, s85, 33
	v_cmp_ge_u32_e64 s[84:85], v162, v12
	v_writelane_b32 v13, s76, 34
	v_writelane_b32 v14, s77, 34
	v_cmp_ge_u32_e64 s[76:77], v125, v12
	v_writelane_b32 v13, s74, 35
	v_writelane_b32 v14, s75, 35
	v_cmp_ge_u32_e64 s[74:75], v164, v12
	v_writelane_b32 v13, s84, 36
	v_writelane_b32 v14, s85, 36
	v_cmp_ge_u32_e64 s[84:85], v159, v12
	v_writelane_b32 v13, s76, 37
	v_writelane_b32 v14, s77, 37
	v_cmp_ge_u32_e64 s[76:77], v168, v12
	v_writelane_b32 v13, s74, 38
	v_writelane_b32 v14, s75, 38
	v_cmp_ge_u32_e64 s[74:75], v161, v12
	v_writelane_b32 v13, s84, 39
	v_writelane_b32 v14, s85, 39
	v_cmp_ge_u32_e64 s[84:85], v170, v12
	v_writelane_b32 v13, s76, 40
	v_writelane_b32 v14, s77, 40
	v_cmp_ge_u32_e64 s[76:77], v163, v12
	v_writelane_b32 v13, s74, 41
	v_writelane_b32 v14, s75, 41
	v_cmp_ge_u32_e64 s[74:75], v172, v12
	v_writelane_b32 v13, s84, 42
	v_writelane_b32 v14, s85, 42
	v_cmp_ge_u32_e64 s[84:85], v165, v12
	v_writelane_b32 v13, s76, 43
	v_writelane_b32 v14, s77, 43
	v_cmp_ge_u32_e64 s[76:77], v174, v12
	v_writelane_b32 v13, s74, 44
	v_writelane_b32 v14, s75, 44
	v_cmp_ge_u32_e64 s[74:75], v169, v12
	v_writelane_b32 v13, s84, 45
	v_writelane_b32 v14, s85, 45
	v_cmp_ge_u32_e64 s[84:85], v176, v12
	v_writelane_b32 v13, s76, 46
	v_writelane_b32 v14, s77, 46
	v_cmp_ge_u32_e64 s[76:77], v171, v12
	v_writelane_b32 v13, s74, 47
	v_writelane_b32 v14, s75, 47
	v_cmp_ge_u32_e64 s[74:75], v178, v12
	v_writelane_b32 v13, s84, 48
	v_writelane_b32 v14, s85, 48
	v_cmp_ge_u32_e64 s[84:85], v173, v12
	v_writelane_b32 v13, s76, 49
	v_writelane_b32 v14, s77, 49
	v_cmp_ge_u32_e64 s[76:77], v180, v12
	v_writelane_b32 v13, s74, 50
	v_writelane_b32 v14, s75, 50
	v_cmp_ge_u32_e64 s[74:75], v175, v12
	v_writelane_b32 v13, s84, 51
	v_writelane_b32 v14, s85, 51
	v_cmp_ge_u32_e64 s[84:85], v182, v12
	v_writelane_b32 v13, s76, 52
	v_writelane_b32 v14, s77, 52
	v_cmp_ge_u32_e64 s[76:77], v177, v12
	v_writelane_b32 v13, s74, 53
	v_writelane_b32 v14, s75, 53
	v_cmp_ge_u32_e64 s[74:75], v184, v12
	v_writelane_b32 v13, s84, 54
	v_writelane_b32 v14, s85, 54
	v_cmp_ge_u32_e64 s[84:85], v179, v12
	v_writelane_b32 v13, s76, 55
	v_writelane_b32 v14, s77, 55
	v_cmp_ge_u32_e64 s[76:77], v186, v12
	v_writelane_b32 v13, s74, 56
	v_writelane_b32 v14, s75, 56
	v_cmp_ge_u32_e64 s[74:75], v181, v12
	v_writelane_b32 v13, s84, 57
	v_writelane_b32 v14, s85, 57
	v_cmp_ge_u32_e64 s[84:85], v188, v12
	v_writelane_b32 v13, s76, 58
	v_writelane_b32 v14, s77, 58
	v_cmp_ge_u32_e64 s[76:77], v183, v12
	v_writelane_b32 v13, s74, 59
	v_writelane_b32 v14, s75, 59
	v_cmp_ge_u32_e64 s[74:75], v190, v12
	v_writelane_b32 v13, s84, 60
	v_writelane_b32 v14, s85, 60
	v_cmp_ge_u32_e64 s[84:85], v185, v12
	s_nop 1
	v_writelane_b32 v13, s76, 61
	v_writelane_b32 v14, s77, 61
	v_writelane_b32 v13, s74, 62
	v_writelane_b32 v14, s75, 62
	v_writelane_b32 v13, s84, 63
	v_writelane_b32 v14, s85, 63
	ds_write2st64_b32 v209, v13, v14 offset1:1
	s_mov_b64 s[2:3], 0
	s_branch .LBB0_3695

; __global__ void __launch_bounds__(512, 2) mega_fwd(KArgs a) {
;     ...
; #pragma unroll 1
;     ...
;                     const unsigned cand = tau | (1u << bit);
;                     int c0 = 0, c1 = 0;
; #pragma unroll
;                     for (int jj = 0; jj < 64; ++jj) { const unsigned long long bm = __ballot(key[jj] >= cand); c0 += __popc((unsigned)bm); c1 += __popc((unsigned)(bm >> 32)); }
;                     const int cnt = (lane < 32) ? c0 : c1;
;                     if (cnt >= 256) tau = cand;
;                     done_sel = done_sel || (cnt == 256);
;                     if (__ballot(!done_sel) == 0ull) break;
;                 }
;                 if (all_valid) tau = 1u;
;                 int g0 = 0, g1 = 0, e0 = 0, e1 = 0;
; #pragma unroll
;                 for (int jj = 0; jj < 64; ++jj) {
;                     const unsigned long long bg = __ballot(key[jj] > tau), be = __ballot(key[jj] == tau);
;                     g0 += __popc((unsigned)bg); g1 += __popc((unsigned)(bg >> 32)); e0 += __popc((unsigned)be); e1 += __popc((unsigned)(be >> 32));
;                 }
;                 const int cgt = (lane < 32) ? g0 : g1, ceq = (lane < 32) ? e0 : e1;
;                 const int need_eq = all_valid ? (1 << 20) : 256 - cgt;
;                 const bool ties = (!all_valid) && (ceq > need_eq);
;                 unsigned w0 = 0u, w1 = 0u;
;                 if (__ballot(ties) == 0ull) {
; #pragma unroll
;                     for (int jj = 0; jj < 64; ++jj) {
;                         const unsigned long long bm = __ballot(key[jj] >= tau);
;                         if (lane == 0) { wscr[jj] = (unsigned)bm; wscr[64 + jj] = (unsigned)(bm >> 32); }
;                     }
.Lmy_sel_loop_3:
	v_lshl_or_b32 v12, 1, v11, v10
	v_mov_b32_e32 v13, 0
	v_cmp_ge_u32_e64 s[84:85], v3, v12
	v_cmp_ge_u32_e64 s[76:77], v2, v12
	v_cmp_ge_u32_e64 s[74:75], v5, v12
	v_addc_co_u32_e64 v13, vcc, 0, v13, s[84:85]
	v_cmp_ge_u32_e64 s[84:85], v4, v12
	v_addc_co_u32_e64 v13, vcc, 0, v13, s[76:77]
	v_cmp_ge_u32_e64 s[76:77], v7, v12
	v_addc_co_u32_e64 v13, vcc, 0, v13, s[74:75]
	v_cmp_ge_u32_e64 s[74:75], v6, v12
	v_addc_co_u32_e64 v13, vcc, 0, v13, s[84:85]
	v_cmp_ge_u32_e64 s[84:85], v9, v12
	v_addc_co_u32_e64 v13, vcc, 0, v13, s[76:77]
	v_cmp_ge_u32_e64 s[76:77], v8, v12
	v_addc_co_u32_e64 v13, vcc, 0, v13, s[74:75]
	v_cmp_ge_u32_e64 s[74:75], v102, v12
	v_addc_co_u32_e64 v13, vcc, 0, v13, s[84:85]
	v_cmp_ge_u32_e64 s[84:85], v97, v12
	v_addc_co_u32_e64 v13, vcc, 0, v13, s[76:77]
	v_cmp_ge_u32_e64 s[76:77], v104, v12
	v_addc_co_u32_e64 v13, vcc, 0, v13, s[74:75]
	v_cmp_ge_u32_e64 s[74:75], v99, v12
	v_addc_co_u32_e64 v13, vcc, 0, v13, s[84:85]
	v_cmp_ge_u32_e64 s[84:85], v106, v12
	v_addc_co_u32_e64 v13, vcc, 0, v13, s[76:77]
	v_cmp_ge_u32_e64 s[76:77], v101, v12
	v_addc_co_u32_e64 v13, vcc, 0, v13, s[74:75]
	v_cmp_ge_u32_e64 s[74:75], v108, v12
	v_addc_co_u32_e64 v13, vcc, 0, v13, s[84:85]
	v_cmp_ge_u32_e64 s[84:85], v103, v12
	v_addc_co_u32_e64 v13, vcc, 0, v13, s[76:77]
	v_cmp_ge_u32_e64 s[76:77], v110, v12
	v_addc_co_u32_e64 v13, vcc, 0, v13, s[74:75]
	v_cmp_ge_u32_e64 s[74:75], v105, v12
	v_addc_co_u32_e64 v13, vcc, 0, v13, s[84:85]
	v_cmp_ge_u32_e64 s[84:85], v112, v12
	v_addc_co_u32_e64 v13, vcc, 0, v13, s[76:77]
	v_cmp_ge_u32_e64 s[76:77], v107, v12
	v_addc_co_u32_e64 v13, vcc, 0, v13, s[74:75]
	v_cmp_ge_u32_e64 s[74:75], v114, v12
	v_addc_co_u32_e64 v13, vcc, 0, v13, s[84:85]
	v_cmp_ge_u32_e64 s[84:85], v109, v12
	v_addc_co_u32_e64 v13, vcc, 0, v13, s[76:77]
	v_cmp_ge_u32_e64 s[76:77], v116, v12
	v_addc_co_u32_e64 v13, vcc, 0, v13, s[74:75]
	v_cmp_ge_u32_e64 s[74:75], v111, v12
	s_nop 1
	v_addc_co_u32_e64 v13, vcc, 0, v13, s[84:85]
	v_addc_co_u32_e64 v13, vcc, 0, v13, s[76:77]
	v_addc_co_u32_e64 v13, vcc, 0, v13, s[74:75]
	s_nop 1
	v_add_u32_dpp v13, v13, v13 quad_perm:[1,0,3,2] row_mask:0xf bank_mask:0xf
	s_nop 1
	v_add_u32_dpp v13, v13, v13 quad_perm:[2,3,0,1] row_mask:0xf bank_mask:0xf
	s_nop 1
	v_add_u32_dpp v13, v13, v13 row_half_mirror row_mask:0xf bank_mask:0xf
	s_nop 1
	v_add_u32_dpp v13, v13, v13 row_mirror row_mask:0xf bank_mask:0xf
	v_mov_b32_e32 v14, v13
	s_nop 1
	v_permlane16_swap_b32 v14, v13
	v_add_u32_e32 v13, v13, v14
	s_movk_i32 s2, 0xff
	v_cmp_lt_i32_e32 vcc, s2, v13
	s_nop 1
	v_cndmask_b32_e32 v10, v10, v12, vcc
	v_cmp_eq_u32_e32 vcc, s5, v13
	s_or_b64 s[0:1], s[0:1], vcc
	s_xor_b64 s[2:3], s[0:1], -1
	v_cndmask_b32_e64 v12, 0, 1, s[2:3]
	v_cmp_ne_u32_e32 vcc, 0, v12
	s_cmp_lg_u64 vcc, 0
	s_cselect_b64 s[2:3], -1, 0
	v_add_co_u32_e32 v11, vcc, -1, v11
	s_and_b64 s[2:3], s[2:3], vcc
	s_and_b64 vcc, exec, s[2:3]
	s_cbranch_vccnz .Lmy_sel_loop_3
	s_andn2_b64 s[2:3], exec, s[0:1]
	s_cbranch_scc0 .Lmy_sel_fast_3
	s_branch .Lmy_sel_slow
.Lmy_isl_r1:
	s_branch .Lmy_isl_r2
.Lmy_sel_fast_3:
	v_cndmask_b32_e64 v12, v10, 1, s[86:87]
	v_mov_b32_e32 v13, 0
	v_mov_b32_e32 v14, 0
	v_cmp_ge_u32_e64 s[84:85], v3, v12
	v_cmp_ge_u32_e64 s[76:77], v2, v12
	v_cmp_ge_u32_e64 s[74:75], v5, v12
	v_writelane_b32 v13, s84, 0
	v_writelane_b32 v14, s85, 0
	v_cmp_ge_u32_e64 s[84:85], v4, v12
	v_writelane_b32 v13, s76, 1
	v_writelane_b32 v14, s77, 1
	v_cmp_ge_u32_e64 s[76:77], v7, v12
	v_writelane_b32 v13, s74, 2
	v_writelane_b32 v14, s75, 2
	v_cmp_ge_u32_e64 s[74:75], v6, v12
	v_writelane_b32 v13, s84, 3
	v_writelane_b32 v14, s85, 3
	v_cmp_ge_u32_e64 s[84:85], v9, v12
	v_writelane_b32 v13, s76, 4
	v_writelane_b32 v14, s77, 4
	v_cmp_ge_u32_e64 s[76:77], v8, v12
	v_writelane_b32 v13, s74, 5
	v_writelane_b32 v14, s75, 5
	v_cmp_ge_u32_e64 s[74:75], v102, v12
	v_writelane_b32 v13, s84, 6
	v_writelane_b32 v14, s85, 6
	v_cmp_ge_u32_e64 s[84:85], v97, v12
	v_writelane_b32 v13, s76, 7
	v_writelane_b32 v14, s77, 7
	v_cmp_ge_u32_e64 s[76:77], v104, v12
	v_writelane_b32 v13, s74, 8
	v_writelane_b32 v14, s75, 8
	v_cmp_ge_u32_e64 s[74:75], v99, v12
	v_writelane_b32 v13, s84, 9
	v_writelane_b32 v14, s85, 9
	v_cmp_ge_u32_e64 s[84:85], v106, v12
	v_writelane_b32 v13, s76, 10
	v_writelane_b32 v14, s77, 10
	v_cmp_ge_u32_e64 s[76:77], v101, v12
	v_writelane_b32 v13, s74, 11
	v_writelane_b32 v14, s75, 11
	v_cmp_ge_u32_e64 s[74:75], v108, v12
	v_writelane_b32 v13, s84, 12
	v_writelane_b32 v14, s85, 12
	v_cmp_ge_u32_e64 s[84:85], v103, v12
	v_writelane_b32 v13, s76, 13
	v_writelane_b32 v14, s77, 13
	v_cmp_ge_u32_e64 s[76:77], v110, v12
	v_writelane_b32 v13, s74, 14
	v_writelane_b32 v14, s75, 14
	v_cmp_ge_u32_e64 s[74:75], v105, v12
	v_writelane_b32 v13, s84, 15
	v_writelane_b32 v14, s85, 15
	v_cmp_ge_u32_e64 s[84:85], v112, v12
	v_writelane_b32 v13, s76, 16
	v_writelane_b32 v14, s77, 16
	v_cmp_ge_u32_e64 s[76:77], v107, v12
	v_writelane_b32 v13, s74, 17
	v_writelane_b32 v14, s75, 17
	v_cmp_ge_u32_e64 s[74:75], v114, v12
	v_writelane_b32 v13, s84, 18
	v_writelane_b32 v14, s85, 18
	v_cmp_ge_u32_e64 s[84:85], v109, v12
	v_writelane_b32 v13, s76, 19
	v_writelane_b32 v14, s77, 19
	v_cmp_ge_u32_e64 s[76:77], v116, v12
	v_writelane_b32 v13, s74, 20
	v_writelane_b32 v14, s75, 20
	v_cmp_ge_u32_e64 s[74:75], v111, v12
	s_nop 1
	v_writelane_b32 v13, s84, 21
	v_writelane_b32 v14, s85, 21
	v_writelane_b32 v13, s76, 22
	v_writelane_b32 v14, s77, 22
	v_writelane_b32 v13, s74, 23
	v_writelane_b32 v14, s75, 23
	ds_write2st64_b32 v209, v13, v14 offset1:1
	s_mov_b64 s[2:3], 0
	s_branch .LBB0_3695

; __device__ __forceinline__ void xcd_barrier(const XcdBarrier& b) {
;     ...
;     if (b.tid == 0u) {
;         unsigned* bar = b.bar;
;         __builtin_amdgcn_s_waitcnt(0);
;         unsigned nloc = b.st[0], nx = b.st[1];
;         if (nloc == 0u) { xcd_barrier_complete(bar, b.x, nloc, nx); b.st[0] = nloc; b.st[1] = nx; }
.Lmy_isl_f1:
	s_branch .Lmy_isl_f2
.LBB0_4174:
	s_and_b64 vcc, exec, s[44:45]
	s_cbranch_vccnz .LBB0_4182

.LBB0_4275:
	global_load_dword v2, v0, s[6:7] sc1
	s_add_i32 s22, s22, 1
	s_mov_b64 s[18:19], -1
	s_waitcnt vmcnt(0)
	v_cmp_ne_u32_e32 vcc, v2, v1
	s_orn2_b64 s[16:17], vcc, exec
	s_branch .LBB0_4270
.Lmy_isl_r2:
	s_branch .Lmy_conv4_done
.LBB0_4276:
	s_cmp_lt_u32 s22, 0x40001
	s_mov_b64 s[18:19], 0
	s_cselect_b64 s[20:21], -1, 0
	s_and_b64 vcc, exec, s[20:21]
	s_cbranch_vccz .LBB0_4270
	s_branch .LBB0_4275

; #define KA_DEF const __attribute__((address_space(4))) KArgs* ka_ = (const __attribute__((address_space(4))) KArgs*)__builtin_amdgcn_kernarg_segment_ptr(); asm volatile("" : "+s"(ka_));
; #define SSQ ((float*)WSP(WS_SSQ))
; __global__ void __launch_bounds__(512, 2) mega_fwd(KArgs a) {
;     ...
;         { KA_DEF pg8::EpiSwiGLU E{RA, FF, SSQ}; run_gemm(TIDX, lds, XB, Wl + WO_13B, T_, 2 * FF, 1024, E); }
.LBB0_4823:
	s_or_b64 exec, exec, s[0:1]
	s_mov_b64 s[0:1], s[88:89]
	s_waitcnt lgkmcnt(0)
	s_barrier
	s_cmpk_lt_u32 s86, 0x80
	s_cbranch_scc1 .Lmy_ffn2up_go
	v_readlane_b32 vcc_lo, v252, 26
	s_nop 1
	s_cmp_eq_u32 vcc_lo, 3
	s_cbranch_scc1 .Lmy_ffn2up_go
	v_writelane_b32 v254, 3, 40
	s_add_i32 vcc_lo, vcc_lo, 1
	s_and_b32 vcc_lo, vcc_lo, 1
	v_writelane_b32 v254, vcc_lo, 41
	s_branch .Lmy_isl_f1
